# v9: v7 + nt hint on gate/up epilogue stores
# baseline (speedup 1.0000x reference)
.LBB0_274:
	s_lshl_b32 s14, s44, 10
	v_add_u32_e32 v147, s14, v142
	ds_read_b32 v147, v147
	v_pk_mul_f32 v[118:119], v[126:127], v[118:119]
	v_pk_mul_f32 v[120:121], v[128:129], v[120:121]
	v_pk_mul_f32 v[114:115], v[122:123], v[114:115]
	v_lshl_or_b32 v148, s45, 7, v144
	s_waitcnt lgkmcnt(0)
	v_mul_f32_e32 v150, 0xbfb8aa3b, v147
	v_pk_mul_f32 v[154:155], v[126:127], v[150:151] op_sel_hi:[1,0]
	v_mul_f32_e32 v152, v147, v147
	v_exp_f32_e32 v154, v154
	v_exp_f32_e32 v155, v155
	v_pk_mul_f32 v[116:117], v[124:125], v[116:117]
	v_lshl_add_u32 v146, s46, 8, v140
	v_ashrrev_i32_e32 v149, 31, v148
	v_pk_add_f32 v[154:155], v[154:155], 1.0 op_sel_hi:[1,0]
	v_pk_mul_f32 v[102:103], v[110:111], v[102:103]
	v_rcp_f32_e32 v154, v154
	v_rcp_f32_e32 v155, v155
	v_pk_mul_f32 v[104:105], v[112:113], v[104:105]
	v_pk_mul_f32 v[98:99], v[106:107], v[98:99]
	v_pk_mul_f32 v[100:101], v[108:109], v[100:101]
	v_pk_mul_f32 v[126:127], v[152:153], v[154:155] op_sel_hi:[0,1]
	v_pk_mul_f32 v[118:119], v[118:119], v[126:127]
	v_pk_mul_f32 v[126:127], v[128:129], v[150:151] op_sel_hi:[1,0]
	v_cvt_pk_bf16_f32 v118, v118, v119
	v_exp_f32_e32 v126, v126
	v_exp_f32_e32 v127, v127
	v_pk_mul_f32 v[84:85], v[92:93], v[84:85]
	v_pk_mul_f32 v[86:87], v[94:95], v[86:87]
	v_pk_mul_f32 v[80:81], v[88:89], v[80:81]
	v_pk_add_f32 v[126:127], v[126:127], 1.0 op_sel_hi:[1,0]
	v_pk_mul_f32 v[82:83], v[90:91], v[82:83]
	v_rcp_f32_e32 v126, v126
	v_rcp_f32_e32 v127, v127
	v_pk_mul_f32 v[68:69], v[76:77], v[68:69]
	v_pk_mul_f32 v[70:71], v[78:79], v[70:71]
	v_pk_mul_f32 v[64:65], v[72:73], v[64:65]
	v_pk_mul_f32 v[126:127], v[152:153], v[126:127] op_sel_hi:[0,1]
	v_pk_mul_f32 v[120:121], v[120:121], v[126:127]
	v_pk_mul_f32 v[126:127], v[122:123], v[150:151] op_sel_hi:[1,0]
	v_cvt_pk_bf16_f32 v119, v120, v121
	v_exp_f32_e32 v126, v126
	v_exp_f32_e32 v127, v127
	v_pk_mul_f32 v[66:67], v[74:75], v[66:67]
	v_pk_mul_f32 v[52:53], v[60:61], v[52:53]
	v_pk_mul_f32 v[54:55], v[62:63], v[54:55]
	v_pk_add_f32 v[126:127], v[126:127], 1.0 op_sel_hi:[1,0]
	v_pk_mul_f32 v[48:49], v[56:57], v[48:49]
	v_rcp_f32_e32 v126, v126
	v_rcp_f32_e32 v127, v127
	v_pk_mul_f32 v[50:51], v[58:59], v[50:51]
	v_pk_mul_f32 v[36:37], v[44:45], v[36:37]
	v_pk_mul_f32 v[38:39], v[46:47], v[38:39]
	v_pk_mul_f32 v[122:123], v[152:153], v[126:127] op_sel_hi:[0,1]
	v_pk_mul_f32 v[114:115], v[114:115], v[122:123]
	v_pk_mul_f32 v[122:123], v[124:125], v[150:151] op_sel_hi:[1,0]
	v_cvt_pk_bf16_f32 v120, v114, v115
	v_exp_f32_e32 v122, v122
	v_exp_f32_e32 v123, v123
	v_mov_b64_e32 v[114:115], s[6:7]
	v_pk_mul_f32 v[32:33], v[40:41], v[32:33]
	v_pk_mul_f32 v[34:35], v[42:43], v[34:35]
	v_pk_add_f32 v[122:123], v[122:123], 1.0 op_sel_hi:[1,0]
	v_pk_mul_f32 v[20:21], v[28:29], v[20:21]
	v_rcp_f32_e32 v122, v122
	v_rcp_f32_e32 v123, v123
	v_pk_mul_f32 v[22:23], v[30:31], v[22:23]
	v_pk_mul_f32 v[16:17], v[24:25], v[16:17]
	v_pk_mul_f32 v[18:19], v[26:27], v[18:19]
	v_pk_mul_f32 v[122:123], v[152:153], v[122:123] op_sel_hi:[0,1]
	v_pk_mul_f32 v[116:117], v[116:117], v[122:123]
	v_mad_i64_i32 v[122:123], s[26:27], v146, s48, v[114:115]
	v_cvt_pk_bf16_f32 v121, v116, v117
	v_lshlrev_b64 v[116:117], 1, v[148:149]
	v_lshl_add_u64 v[122:123], v[122:123], 0, v[116:117]
	global_store_dwordx4 v[122:123], v[118:121], off nt
	v_pk_mul_f32 v[8:9], v[12:13], v[8:9]
	v_pk_mul_f32 v[10:11], v[14:15], v[10:11]
	v_add_u32_e32 v118, s14, v143
	v_add_u32_e32 v119, 0x20040, v118
	ds_read_b32 v119, v119
	v_pk_mul_f32 v[0:1], v[4:5], v[0:1]
	v_pk_mul_f32 v[2:3], v[6:7], v[2:3]
	s_andn2_b64 vcc, exec, s[0:1]
	s_waitcnt lgkmcnt(0)
	v_mul_f32_e32 v120, 0xbfb8aa3b, v119
	v_pk_mul_f32 v[124:125], v[110:111], v[120:121] op_sel_hi:[1,0]
	v_mul_f32_e32 v122, v119, v119
	v_exp_f32_e32 v124, v124
	v_exp_f32_e32 v125, v125
	s_nop 0
	v_pk_add_f32 v[124:125], v[124:125], 1.0 op_sel_hi:[1,0]
	s_nop 0
	v_rcp_f32_e32 v124, v124
	v_rcp_f32_e32 v125, v125
	s_nop 0
	v_pk_mul_f32 v[110:111], v[122:123], v[124:125] op_sel_hi:[0,1]
	v_pk_mul_f32 v[102:103], v[102:103], v[110:111]
	v_pk_mul_f32 v[110:111], v[112:113], v[120:121] op_sel_hi:[1,0]
	s_nop 0
	v_exp_f32_e32 v110, v110
	v_exp_f32_e32 v111, v111
	s_nop 0
	v_pk_add_f32 v[110:111], v[110:111], 1.0 op_sel_hi:[1,0]
	s_nop 0
	v_rcp_f32_e32 v110, v110
	v_rcp_f32_e32 v111, v111
	s_nop 0
	v_pk_mul_f32 v[110:111], v[122:123], v[110:111] op_sel_hi:[0,1]
	v_pk_mul_f32 v[104:105], v[104:105], v[110:111]
	v_pk_mul_f32 v[110:111], v[106:107], v[120:121] op_sel_hi:[1,0]
	s_nop 0
	v_exp_f32_e32 v110, v110
	v_exp_f32_e32 v111, v111
	s_nop 0
	v_pk_add_f32 v[110:111], v[110:111], 1.0 op_sel_hi:[1,0]
	s_nop 0
	v_rcp_f32_e32 v110, v110
	v_rcp_f32_e32 v111, v111
	s_nop 0
	v_pk_mul_f32 v[106:107], v[122:123], v[110:111] op_sel_hi:[0,1]
	v_pk_mul_f32 v[106:107], v[98:99], v[106:107]
	v_pk_mul_f32 v[98:99], v[108:109], v[120:121] op_sel_hi:[1,0]
	v_or_b32_e32 v110, 16, v146
	v_exp_f32_e32 v98, v98
	v_exp_f32_e32 v99, v99
	s_nop 0
	v_pk_add_f32 v[98:99], v[98:99], 1.0 op_sel_hi:[1,0]
	s_nop 0
	v_rcp_f32_e32 v98, v98
	v_rcp_f32_e32 v99, v99
	s_nop 0
	v_pk_mul_f32 v[98:99], v[122:123], v[98:99] op_sel_hi:[0,1]
	v_pk_mul_f32 v[108:109], v[100:101], v[98:99]
	v_cvt_pk_bf16_f32 v98, v102, v103
	v_mad_i64_i32 v[102:103], s[14:15], v110, s48, v[114:115]
	v_cvt_pk_bf16_f32 v99, v104, v105
	v_cvt_pk_bf16_f32 v100, v106, v107
	v_cvt_pk_bf16_f32 v101, v108, v109
	v_lshl_add_u64 v[102:103], v[102:103], 0, v[116:117]
	global_store_dwordx4 v[102:103], v[98:101], off nt
	s_nop 1
	v_add_u32_e32 v98, 0x20080, v118
	ds_read_b32 v99, v98
	s_waitcnt lgkmcnt(0)
	v_mul_f32_e32 v98, 0xbfb8aa3b, v99
	v_pk_mul_f32 v[102:103], v[92:93], v[98:99] op_sel_hi:[1,0]
	v_mul_f32_e32 v100, v99, v99
	v_exp_f32_e32 v102, v102
	v_exp_f32_e32 v103, v103
	s_nop 0
	v_pk_add_f32 v[102:103], v[102:103], 1.0 op_sel_hi:[1,0]
	s_nop 0
	v_rcp_f32_e32 v102, v102
	v_rcp_f32_e32 v103, v103
	s_nop 0
	v_pk_mul_f32 v[92:93], v[100:101], v[102:103] op_sel_hi:[0,1]
	v_pk_mul_f32 v[84:85], v[84:85], v[92:93]
	v_pk_mul_f32 v[92:93], v[94:95], v[98:99] op_sel_hi:[1,0]
	s_nop 0
	v_exp_f32_e32 v92, v92
	v_exp_f32_e32 v93, v93
	s_nop 0
	v_pk_add_f32 v[92:93], v[92:93], 1.0 op_sel_hi:[1,0]
	s_nop 0
	v_rcp_f32_e32 v92, v92
	v_rcp_f32_e32 v93, v93
	s_nop 0
	v_pk_mul_f32 v[92:93], v[100:101], v[92:93] op_sel_hi:[0,1]
	v_pk_mul_f32 v[86:87], v[86:87], v[92:93]
	v_pk_mul_f32 v[92:93], v[88:89], v[98:99] op_sel_hi:[1,0]
	s_nop 0
	v_exp_f32_e32 v92, v92
	v_exp_f32_e32 v93, v93
	s_nop 0
	v_pk_add_f32 v[92:93], v[92:93], 1.0 op_sel_hi:[1,0]
	s_nop 0
	v_rcp_f32_e32 v92, v92
	v_rcp_f32_e32 v93, v93
	s_nop 0
	v_pk_mul_f32 v[88:89], v[100:101], v[92:93] op_sel_hi:[0,1]
	v_pk_mul_f32 v[88:89], v[80:81], v[88:89]
	v_pk_mul_f32 v[80:81], v[90:91], v[98:99] op_sel_hi:[1,0]
	v_or_b32_e32 v92, 32, v146
	v_exp_f32_e32 v80, v80
	v_exp_f32_e32 v81, v81
	s_nop 0
	v_pk_add_f32 v[80:81], v[80:81], 1.0 op_sel_hi:[1,0]
	s_nop 0
	v_rcp_f32_e32 v80, v80
	v_rcp_f32_e32 v81, v81
	s_nop 0
	v_pk_mul_f32 v[80:81], v[100:101], v[80:81] op_sel_hi:[0,1]
	v_pk_mul_f32 v[90:91], v[82:83], v[80:81]
	v_cvt_pk_bf16_f32 v80, v84, v85
	v_mad_i64_i32 v[84:85], s[14:15], v92, s48, v[114:115]
	v_cvt_pk_bf16_f32 v81, v86, v87
	v_cvt_pk_bf16_f32 v82, v88, v89
	v_cvt_pk_bf16_f32 v83, v90, v91
	v_lshl_add_u64 v[84:85], v[84:85], 0, v[116:117]
	global_store_dwordx4 v[84:85], v[80:83], off nt
	s_nop 1
	v_add_u32_e32 v80, 0x200c0, v118
	ds_read_b32 v81, v80
	s_waitcnt lgkmcnt(0)
	v_mul_f32_e32 v80, 0xbfb8aa3b, v81
	v_pk_mul_f32 v[84:85], v[76:77], v[80:81] op_sel_hi:[1,0]
	v_mul_f32_e32 v82, v81, v81
	v_exp_f32_e32 v84, v84
	v_exp_f32_e32 v85, v85
	s_nop 0
	v_pk_add_f32 v[84:85], v[84:85], 1.0 op_sel_hi:[1,0]
	s_nop 0
	v_rcp_f32_e32 v84, v84
	v_rcp_f32_e32 v85, v85
	s_nop 0
	v_pk_mul_f32 v[76:77], v[82:83], v[84:85] op_sel_hi:[0,1]
	v_pk_mul_f32 v[68:69], v[68:69], v[76:77]
	v_pk_mul_f32 v[76:77], v[78:79], v[80:81] op_sel_hi:[1,0]
	s_nop 0
	v_exp_f32_e32 v76, v76
	v_exp_f32_e32 v77, v77
	s_nop 0
	v_pk_add_f32 v[76:77], v[76:77], 1.0 op_sel_hi:[1,0]
	s_nop 0
	v_rcp_f32_e32 v76, v76
	v_rcp_f32_e32 v77, v77
	s_nop 0
	v_pk_mul_f32 v[76:77], v[82:83], v[76:77] op_sel_hi:[0,1]
	v_pk_mul_f32 v[70:71], v[70:71], v[76:77]
	v_pk_mul_f32 v[76:77], v[72:73], v[80:81] op_sel_hi:[1,0]
	s_nop 0
	v_exp_f32_e32 v76, v76
	v_exp_f32_e32 v77, v77
	s_nop 0
	v_pk_add_f32 v[76:77], v[76:77], 1.0 op_sel_hi:[1,0]
	s_nop 0
	v_rcp_f32_e32 v76, v76
	v_rcp_f32_e32 v77, v77
	s_nop 0
	v_pk_mul_f32 v[72:73], v[82:83], v[76:77] op_sel_hi:[0,1]
	v_pk_mul_f32 v[72:73], v[64:65], v[72:73]
	v_pk_mul_f32 v[64:65], v[74:75], v[80:81] op_sel_hi:[1,0]
	v_or_b32_e32 v76, 48, v146
	v_exp_f32_e32 v64, v64
	v_exp_f32_e32 v65, v65
	s_nop 0
	v_pk_add_f32 v[64:65], v[64:65], 1.0 op_sel_hi:[1,0]
	s_nop 0
	v_rcp_f32_e32 v64, v64
	v_rcp_f32_e32 v65, v65
	s_nop 0
	v_pk_mul_f32 v[64:65], v[82:83], v[64:65] op_sel_hi:[0,1]
	v_pk_mul_f32 v[74:75], v[66:67], v[64:65]
	v_cvt_pk_bf16_f32 v64, v68, v69
	v_mad_i64_i32 v[68:69], s[14:15], v76, s48, v[114:115]
	v_cvt_pk_bf16_f32 v65, v70, v71
	v_cvt_pk_bf16_f32 v66, v72, v73
	v_cvt_pk_bf16_f32 v67, v74, v75
	v_lshl_add_u64 v[68:69], v[68:69], 0, v[116:117]
	global_store_dwordx4 v[68:69], v[64:67], off nt
	s_nop 1
	v_add_u32_e32 v64, 0x20200, v118
	ds_read_b32 v66, v64
	v_add_u32_e32 v65, 0x80, v146
	s_waitcnt lgkmcnt(0)
	v_mul_f32_e32 v64, 0xbfb8aa3b, v66
	v_pk_mul_f32 v[68:69], v[60:61], v[64:65] op_sel_hi:[1,0]
	v_mul_f32_e32 v66, v66, v66
	v_exp_f32_e32 v68, v68
	v_exp_f32_e32 v69, v69
	s_nop 0
	v_pk_add_f32 v[68:69], v[68:69], 1.0 op_sel_hi:[1,0]
	s_nop 0
	v_rcp_f32_e32 v68, v68
	v_rcp_f32_e32 v69, v69
	s_nop 0
	v_pk_mul_f32 v[60:61], v[66:67], v[68:69] op_sel_hi:[0,1]
	v_pk_mul_f32 v[52:53], v[52:53], v[60:61]
	v_pk_mul_f32 v[60:61], v[62:63], v[64:65] op_sel_hi:[1,0]
	s_nop 0
	v_exp_f32_e32 v60, v60
	v_exp_f32_e32 v61, v61
	s_nop 0
	v_pk_add_f32 v[60:61], v[60:61], 1.0 op_sel_hi:[1,0]
	s_nop 0
	v_rcp_f32_e32 v60, v60
	v_rcp_f32_e32 v61, v61
	s_nop 0
	v_pk_mul_f32 v[60:61], v[66:67], v[60:61] op_sel_hi:[0,1]
	v_pk_mul_f32 v[54:55], v[54:55], v[60:61]
	v_pk_mul_f32 v[60:61], v[56:57], v[64:65] op_sel_hi:[1,0]
	s_nop 0
	v_exp_f32_e32 v60, v60
	v_exp_f32_e32 v61, v61
	s_nop 0
	v_pk_add_f32 v[60:61], v[60:61], 1.0 op_sel_hi:[1,0]
	s_nop 0
	v_rcp_f32_e32 v60, v60
	v_rcp_f32_e32 v61, v61
	s_nop 0
	v_pk_mul_f32 v[56:57], v[66:67], v[60:61] op_sel_hi:[0,1]
	v_pk_mul_f32 v[56:57], v[48:49], v[56:57]
	v_pk_mul_f32 v[48:49], v[58:59], v[64:65] op_sel_hi:[1,0]
	s_nop 0
	v_exp_f32_e32 v48, v48
	v_exp_f32_e32 v49, v49
	s_nop 0
	v_pk_add_f32 v[48:49], v[48:49], 1.0 op_sel_hi:[1,0]
	s_nop 0
	v_rcp_f32_e32 v48, v48
	v_rcp_f32_e32 v49, v49
	s_nop 0
	v_pk_mul_f32 v[48:49], v[66:67], v[48:49] op_sel_hi:[0,1]
	v_pk_mul_f32 v[58:59], v[50:51], v[48:49]
	v_cvt_pk_bf16_f32 v48, v52, v53
	v_mad_i64_i32 v[52:53], s[14:15], v65, s48, v[114:115]
	v_cvt_pk_bf16_f32 v49, v54, v55
	v_cvt_pk_bf16_f32 v50, v56, v57
	v_cvt_pk_bf16_f32 v51, v58, v59
	v_lshl_add_u64 v[52:53], v[52:53], 0, v[116:117]
	global_store_dwordx4 v[52:53], v[48:51], off nt
	s_nop 1
	v_add_u32_e32 v48, 0x20240, v118
	ds_read_b32 v49, v48
	s_waitcnt lgkmcnt(0)
	v_mul_f32_e32 v48, 0xbfb8aa3b, v49
	v_pk_mul_f32 v[52:53], v[44:45], v[48:49] op_sel_hi:[1,0]
	v_mul_f32_e32 v50, v49, v49
	v_exp_f32_e32 v52, v52
	v_exp_f32_e32 v53, v53
	s_nop 0
	v_pk_add_f32 v[52:53], v[52:53], 1.0 op_sel_hi:[1,0]
	s_nop 0
	v_rcp_f32_e32 v52, v52
	v_rcp_f32_e32 v53, v53
	s_nop 0
	v_pk_mul_f32 v[44:45], v[50:51], v[52:53] op_sel_hi:[0,1]
	v_pk_mul_f32 v[36:37], v[36:37], v[44:45]
	v_pk_mul_f32 v[44:45], v[46:47], v[48:49] op_sel_hi:[1,0]
	s_nop 0
	v_exp_f32_e32 v44, v44
	v_exp_f32_e32 v45, v45
	s_nop 0
	v_pk_add_f32 v[44:45], v[44:45], 1.0 op_sel_hi:[1,0]
	s_nop 0
	v_rcp_f32_e32 v44, v44
	v_rcp_f32_e32 v45, v45
	s_nop 0
	v_pk_mul_f32 v[44:45], v[50:51], v[44:45] op_sel_hi:[0,1]
	v_pk_mul_f32 v[38:39], v[38:39], v[44:45]
	v_pk_mul_f32 v[44:45], v[40:41], v[48:49] op_sel_hi:[1,0]
	s_nop 0
	v_exp_f32_e32 v44, v44
	v_exp_f32_e32 v45, v45
	s_nop 0
	v_pk_add_f32 v[44:45], v[44:45], 1.0 op_sel_hi:[1,0]
	s_nop 0
	v_rcp_f32_e32 v44, v44
	v_rcp_f32_e32 v45, v45
	s_nop 0
	v_pk_mul_f32 v[40:41], v[50:51], v[44:45] op_sel_hi:[0,1]
	v_pk_mul_f32 v[40:41], v[32:33], v[40:41]
	v_pk_mul_f32 v[32:33], v[42:43], v[48:49] op_sel_hi:[1,0]
	v_add_u32_e32 v44, 0x90, v146
	v_exp_f32_e32 v32, v32
	v_exp_f32_e32 v33, v33
	s_nop 0
	v_pk_add_f32 v[32:33], v[32:33], 1.0 op_sel_hi:[1,0]
	s_nop 0
	v_rcp_f32_e32 v32, v32
	v_rcp_f32_e32 v33, v33
	s_nop 0
	v_pk_mul_f32 v[32:33], v[50:51], v[32:33] op_sel_hi:[0,1]
	v_pk_mul_f32 v[42:43], v[34:35], v[32:33]
	v_cvt_pk_bf16_f32 v32, v36, v37
	v_mad_i64_i32 v[36:37], s[14:15], v44, s48, v[114:115]
	v_cvt_pk_bf16_f32 v33, v38, v39
	v_cvt_pk_bf16_f32 v34, v40, v41
	v_cvt_pk_bf16_f32 v35, v42, v43
	v_lshl_add_u64 v[36:37], v[36:37], 0, v[116:117]
	global_store_dwordx4 v[36:37], v[32:35], off nt
	s_nop 1
	v_add_u32_e32 v32, 0x20280, v118
	ds_read_b32 v33, v32
	s_waitcnt lgkmcnt(0)
	v_mul_f32_e32 v32, 0xbfb8aa3b, v33
	v_pk_mul_f32 v[36:37], v[28:29], v[32:33] op_sel_hi:[1,0]
	v_mul_f32_e32 v34, v33, v33
	v_exp_f32_e32 v36, v36
	v_exp_f32_e32 v37, v37
	s_nop 0
	v_pk_add_f32 v[36:37], v[36:37], 1.0 op_sel_hi:[1,0]
	s_nop 0
	v_rcp_f32_e32 v36, v36
	v_rcp_f32_e32 v37, v37
	s_nop 0
	v_pk_mul_f32 v[28:29], v[34:35], v[36:37] op_sel_hi:[0,1]
	v_pk_mul_f32 v[20:21], v[20:21], v[28:29]
	v_pk_mul_f32 v[28:29], v[30:31], v[32:33] op_sel_hi:[1,0]
	s_nop 0
	v_exp_f32_e32 v28, v28
	v_exp_f32_e32 v29, v29
	s_nop 0
	v_pk_add_f32 v[28:29], v[28:29], 1.0 op_sel_hi:[1,0]
	s_nop 0
	v_rcp_f32_e32 v28, v28
	v_rcp_f32_e32 v29, v29
	s_nop 0
	v_pk_mul_f32 v[28:29], v[34:35], v[28:29] op_sel_hi:[0,1]
	v_pk_mul_f32 v[22:23], v[22:23], v[28:29]
	v_pk_mul_f32 v[28:29], v[24:25], v[32:33] op_sel_hi:[1,0]
	s_nop 0
	v_exp_f32_e32 v28, v28
	v_exp_f32_e32 v29, v29
	s_nop 0
	v_pk_add_f32 v[28:29], v[28:29], 1.0 op_sel_hi:[1,0]
	s_nop 0
	v_rcp_f32_e32 v28, v28
	v_rcp_f32_e32 v29, v29
	s_nop 0
	v_pk_mul_f32 v[24:25], v[34:35], v[28:29] op_sel_hi:[0,1]
	v_pk_mul_f32 v[24:25], v[16:17], v[24:25]
	v_pk_mul_f32 v[16:17], v[26:27], v[32:33] op_sel_hi:[1,0]
	v_add_u32_e32 v28, 0xa0, v146
	v_exp_f32_e32 v16, v16
	v_exp_f32_e32 v17, v17
	s_nop 0
	v_pk_add_f32 v[16:17], v[16:17], 1.0 op_sel_hi:[1,0]
	s_nop 0
	v_rcp_f32_e32 v16, v16
	v_rcp_f32_e32 v17, v17
	s_nop 0
	v_pk_mul_f32 v[16:17], v[34:35], v[16:17] op_sel_hi:[0,1]
	v_pk_mul_f32 v[26:27], v[18:19], v[16:17]
	v_cvt_pk_bf16_f32 v16, v20, v21
	v_mad_i64_i32 v[20:21], s[14:15], v28, s48, v[114:115]
	v_cvt_pk_bf16_f32 v17, v22, v23
	v_cvt_pk_bf16_f32 v18, v24, v25
	v_cvt_pk_bf16_f32 v19, v26, v27
	v_lshl_add_u64 v[20:21], v[20:21], 0, v[116:117]
	global_store_dwordx4 v[20:21], v[16:19], off nt
	s_nop 1
	v_add_u32_e32 v16, 0x202c0, v118
	ds_read_b32 v16, v16
	s_waitcnt lgkmcnt(0)
	v_mul_f32_e32 v18, 0xbfb8aa3b, v16
	v_pk_mul_f32 v[20:21], v[12:13], v[18:19] op_sel_hi:[1,0]
	v_mul_f32_e32 v16, v16, v16
	v_exp_f32_e32 v20, v20
	v_exp_f32_e32 v21, v21
	s_nop 0
	v_pk_add_f32 v[20:21], v[20:21], 1.0 op_sel_hi:[1,0]
	s_nop 0
	v_rcp_f32_e32 v20, v20
	v_rcp_f32_e32 v21, v21
	s_nop 0
	v_pk_mul_f32 v[12:13], v[16:17], v[20:21] op_sel_hi:[0,1]
	v_pk_mul_f32 v[8:9], v[8:9], v[12:13]
	v_pk_mul_f32 v[12:13], v[14:15], v[18:19] op_sel_hi:[1,0]
	s_nop 0
	v_exp_f32_e32 v12, v12
	v_exp_f32_e32 v13, v13
	s_nop 0
	v_pk_add_f32 v[12:13], v[12:13], 1.0 op_sel_hi:[1,0]
	s_nop 0
	v_rcp_f32_e32 v12, v12
	v_rcp_f32_e32 v13, v13
	s_nop 0
	v_pk_mul_f32 v[12:13], v[16:17], v[12:13] op_sel_hi:[0,1]
	v_pk_mul_f32 v[10:11], v[10:11], v[12:13]
	v_pk_mul_f32 v[12:13], v[4:5], v[18:19] op_sel_hi:[1,0]
	s_nop 0
	v_exp_f32_e32 v12, v12
	v_exp_f32_e32 v13, v13
	s_nop 0
	v_pk_add_f32 v[12:13], v[12:13], 1.0 op_sel_hi:[1,0]
	s_nop 0
	v_rcp_f32_e32 v12, v12
	v_rcp_f32_e32 v13, v13
	s_nop 0
	v_pk_mul_f32 v[4:5], v[16:17], v[12:13] op_sel_hi:[0,1]
	v_pk_mul_f32 v[4:5], v[0:1], v[4:5]
	v_pk_mul_f32 v[0:1], v[6:7], v[18:19] op_sel_hi:[1,0]
	v_add_u32_e32 v12, 0xb0, v146
	v_exp_f32_e32 v0, v0
	v_exp_f32_e32 v1, v1
	s_nop 0
	v_pk_add_f32 v[0:1], v[0:1], 1.0 op_sel_hi:[1,0]
	s_nop 0
	v_rcp_f32_e32 v0, v0
	v_rcp_f32_e32 v1, v1
	s_nop 0
	v_pk_mul_f32 v[0:1], v[16:17], v[0:1] op_sel_hi:[0,1]
	v_pk_mul_f32 v[6:7], v[2:3], v[0:1]
	v_cvt_pk_bf16_f32 v2, v4, v5
	v_mad_i64_i32 v[4:5], s[14:15], v12, s48, v[114:115]
	v_cvt_pk_bf16_f32 v0, v8, v9
	v_cvt_pk_bf16_f32 v1, v10, v11
	v_cvt_pk_bf16_f32 v3, v6, v7
	v_lshl_add_u64 v[4:5], v[4:5], 0, v[116:117]
	s_mov_b64 s[14:15], -1
	global_store_dwordx4 v[4:5], v[0:3], off nt
	s_cbranch_vccnz .LBB0_267
	s_andn2_b64 vcc, exec, s[4:5]
	s_cbranch_vccnz .LBB0_266
	s_barrier
	s_branch .LBB0_266
